# one static s_setprio 1 for waves 4-7 at kernel entry; all per-phase priority flips removed (GEMM loops and attention)
# baseline (speedup 1.0000x reference)
.LBB0_6:
	s_lshr_b32 s97, s5, 6
	s_cmp_ge_u32 s97, 4
	s_cbranch_scc0 .Lprio_skip
	s_setprio 1
.Lprio_skip:
	s_cmp_gt_i32 s95, -1
	s_cselect_b64 s[0:1], -1, 0
	v_writelane_b32 v254, s0, 3
	v_lshrrev_b32_e32 v2, 20, v0
	v_lshrrev_b32_e32 v0, 10, v0
	v_writelane_b32 v254, s1, 4
	s_and_b32 s0, s5, 0xffffffc0
	v_writelane_b32 v254, s0, 5
	s_add_u32 s0, s64, 0x200
	s_addc_u32 s1, s65, 0
	v_writelane_b32 v254, s0, 6
	v_or_b32_e32 v0, v0, v2
	v_exp_f32_e32 v159, 0xbfd49a78
	v_writelane_b32 v254, s1, 7
	s_add_u32 s0, s64, 0x1000
	s_addc_u32 s1, s65, 0
	v_writelane_b32 v254, s0, 8
	v_exp_f32_e32 v190, 0xc0549a78
	v_exp_f32_e32 v191, 0xc09f73da
	v_writelane_b32 v254, s1, 9
	s_add_u32 s0, s64, 0x1100
	s_addc_u32 s1, s65, 0
	v_writelane_b32 v254, s0, 10
	v_exp_f32_e32 v192, 0xc0d49a78
	v_exp_f32_e32 v193, 0xc104e08b
	v_writelane_b32 v254, s1, 11
	s_add_u32 s0, s64, 0x1200
	s_addc_u32 s1, s65, 0
	v_writelane_b32 v254, s0, 12
	v_exp_f32_e32 v194, 0xc11f73da
	v_exp_f32_e32 v195, 0xc13a0729
	v_writelane_b32 v254, s1, 13
	s_add_u32 s0, s64, 0x1300
	s_addc_u32 s1, s65, 0
	v_writelane_b32 v254, s0, 14
	s_cmp_eq_u32 s4, 15
	s_mov_b32 s8, s94
	v_writelane_b32 v254, s1, 15
	s_cselect_b64 s[0:1], -1, 0
	v_writelane_b32 v254, s0, 16
	s_cmp_eq_u32 s4, 14
	v_writelane_b32 v255, s94, 0
	v_writelane_b32 v254, s1, 17
	s_cselect_b64 s[0:1], -1, 0
	v_writelane_b32 v254, s0, 18
	s_cmp_eq_u32 s4, 13
	v_writelane_b32 v255, s95, 1
	v_writelane_b32 v254, s1, 19
	s_cselect_b64 s[0:1], -1, 0
	v_writelane_b32 v254, s0, 20
	s_cmp_eq_u32 s4, 12
	s_mov_b32 s86, 0xfffe8000
	v_writelane_b32 v254, s1, 21
	s_cselect_b64 s[0:1], -1, 0
	v_writelane_b32 v254, s0, 22
	s_cmp_eq_u32 s4, 11
	v_writelane_b32 v255, s96, 2
	v_writelane_b32 v254, s1, 23
	s_cselect_b64 s[0:1], -1, 0
	v_writelane_b32 v254, s0, 24
	s_cmp_eq_u32 s4, 10
	v_mov_b32_e32 v157, 0
	v_writelane_b32 v254, s1, 25
	s_cselect_b64 s[0:1], -1, 0
	v_writelane_b32 v254, s0, 26
	s_cmp_eq_u32 s4, 9
	v_mov_b32_e32 v196, 1
	v_writelane_b32 v254, s1, 27
	s_cselect_b64 s[0:1], -1, 0
	v_writelane_b32 v254, s0, 28
	s_cmp_eq_u32 s4, 8
	s_mov_b32 s73, 0x8000
	v_writelane_b32 v254, s1, 29
	s_cselect_b64 s[0:1], -1, 0
	v_writelane_b32 v254, s0, 30
	s_cmp_eq_u32 s4, 7
	v_mov_b32_e32 v158, 0x358637bd
	v_writelane_b32 v254, s1, 31
	s_cselect_b64 s[0:1], -1, 0
	v_writelane_b32 v254, s0, 32
	s_cmp_eq_u32 s4, 6
	s_mov_b32 s82, 0x800000
	v_writelane_b32 v254, s1, 33
	s_cselect_b64 s[0:1], -1, 0
	v_writelane_b32 v254, s0, 34
	s_cmp_eq_u32 s4, 5
	s_movk_i32 s90, 0x7fff
	v_writelane_b32 v254, s1, 35
	s_cselect_b64 s[0:1], -1, 0
	v_writelane_b32 v254, s0, 36
	s_cmp_eq_u32 s4, 4
	s_mov_b32 s77, 0x8800
	v_writelane_b32 v254, s1, 37
	s_cselect_b64 s[0:1], -1, 0
	v_writelane_b32 v254, s0, 38
	s_cmp_eq_u32 s4, 3
	s_mov_b32 s70, 0x9000
	v_writelane_b32 v254, s1, 39
	s_cselect_b64 s[0:1], -1, 0
	v_writelane_b32 v254, s0, 40
	s_cmp_eq_u32 s4, 2
	s_movk_i32 s78, 0x600
	v_writelane_b32 v254, s1, 41
	s_cselect_b64 s[0:1], -1, 0
	v_writelane_b32 v254, s0, 42
	s_cmp_eq_u32 s4, 1
	s_movk_i32 s87, 0x1ff
	v_writelane_b32 v254, s1, 43
	s_cselect_b64 s[0:1], -1, 0
	v_writelane_b32 v254, s0, 44
	s_cmp_eq_u32 s4, 0
	v_mov_b32_e32 v198, 0x3b000000
	v_writelane_b32 v254, s1, 45
	s_cselect_b64 s[0:1], -1, 0
	v_writelane_b32 v254, s0, 46
	v_mov_b32_e32 v200, 0x1100
	v_mov_b32_e32 v201, 0xcf
	v_writelane_b32 v254, s1, 47
	s_lshl_b32 s0, s4, 8
	s_add_u32 s0, s64, s0
	s_addc_u32 s1, s65, 0
	s_add_u32 s2, s0, 0x1400
	s_addc_u32 s3, s1, 0
	v_writelane_b32 v254, s2, 48
	s_add_u32 s0, s0, 0x2400
	s_addc_u32 s1, s1, 0
	v_writelane_b32 v254, s3, 49
	v_writelane_b32 v254, s0, 50
	v_mov_b32_e32 v202, 0xfcf
	v_mov_b32_e32 v213, 0x3e16c740
	v_writelane_b32 v254, s1, 51
	s_add_u32 s0, s64, 0x3400
	s_addc_u32 s1, s65, 0
	v_writelane_b32 v254, s0, 52
	v_mov_b32_e32 v204, 0x100
	v_mov_b32_e32 v205, 0x1000
	v_writelane_b32 v254, s1, 53
	s_add_u32 s0, s64, 0x3500
	s_addc_u32 s1, s65, 0
	v_writelane_b32 v254, s0, 54
	v_mov_b32_e32 v199, 0x7fffff00
	v_mov_b32_e32 v203, 0xffffbaa0
	v_writelane_b32 v254, s1, 55
	s_movk_i32 s0, 0x3ff
	v_and_or_b32 v0, v0, s0, v1
	s_add_i32 s0, 0, 0x23ff0
	v_writelane_b32 v254, s0, 56
	s_add_i32 s0, 0, 0x23ff4
	v_writelane_b32 v254, s0, 57
	s_add_i32 s0, 0, 0x1e800
	v_writelane_b32 v254, s0, 58
	s_add_i32 s0, 0, 0x18800
	v_writelane_b32 v254, s0, 59
	v_cmp_eq_u32_e64 s[0:1], 0, v0
	v_mbcnt_lo_u32_b32 v1, -1, 0
	v_mbcnt_hi_u32_b32 v197, -1, v1
	v_writelane_b32 v254, s0, 60
	v_mov_b32_e32 v210, 0xfffff500
	v_mov_b32_e32 v211, 0x80
	v_writelane_b32 v254, s1, 61
	v_writelane_b32 v254, s92, 62
	v_mov_b32_e32 v212, 0x7f800000
	s_movk_i32 s53, 0x60
	s_movk_i32 s23, 0xc0
	s_movk_i32 s75, 0x5800
	s_movk_i32 s58, 0x80
	s_movk_i32 s22, 0xaff
	s_movk_i32 s33, 0x1600
	s_movk_i32 s59, 0x63
	s_movk_i32 s83, 0x24af
	s_mov_b32 s71, 0xaaaaaaab
	s_add_i32 s72, 0, 0x1c800
	s_add_i32 s76, 0, 0x10800
	s_movk_i32 s91, 0xdff
	s_mov_b32 s11, 0
	s_mov_b64 s[50:51], 0x80
	s_mov_b64 s[4:5], 0x3000
	s_mov_b64 s[12:13], 0x5ffff
	s_mov_b64 s[14:15], 0xffff
	s_mov_b64 s[16:17], 0x800
	s_mov_b32 s52, 0x3f803f80
	v_writelane_b32 v254, s93, 63
	v_writelane_b32 v255, s97, 3
	s_branch .LBB0_8

.LBB0_161:
	v_add3_u32 v96, s10, v110, v142
	ds_read_b128 v[64:67], v96
	ds_read_b128 v[68:71], v96 offset:64
	ds_read_b128 v[72:75], v96 offset:128
	v_mov_b32_e32 v131, v130
	v_mov_b32_e32 v129, v128
	s_waitcnt lgkmcnt(2)
	v_mfma_f32_16x16x32_bf16 v[76:79], v[64:67], v[0:3], 0
	s_mov_b32 s53, s52
	s_mov_b32 s54, s52
	s_mov_b32 s55, s52
	v_mfma_f32_16x16x32_bf16 v[64:67], v[64:67], v[8:11], 0
	v_mov_b32_e32 v127, v157
	s_add_i32 s9, s9, s18
	s_waitcnt lgkmcnt(1)
	v_mfma_f32_16x16x32_bf16 v[76:79], v[68:71], v[4:7], v[76:79]
	v_mfma_f32_16x16x32_bf16 v[64:67], v[68:71], v[12:15], v[64:67]
	s_waitcnt lgkmcnt(0)
	v_mfma_f32_16x16x32_bf16 v[76:79], v[72:75], v[16:19], v[76:79]
	v_mfma_f32_16x16x32_bf16 v[64:67], v[72:75], v[20:23], v[64:67]
	ds_read_b128 v[68:71], v96 offset:3328
	ds_read_b128 v[72:75], v96 offset:3392
	ds_read_b128 v[80:83], v96 offset:3456
	s_waitcnt lgkmcnt(2)
	v_mfma_f32_16x16x32_bf16 v[84:87], v[68:71], v[0:3], 0
	v_mfma_f32_16x16x32_bf16 v[68:71], v[68:71], v[8:11], 0
	s_waitcnt lgkmcnt(1)
	v_mfma_f32_16x16x32_bf16 v[84:87], v[72:75], v[4:7], v[84:87]
	v_mfma_f32_16x16x32_bf16 v[68:71], v[72:75], v[12:15], v[68:71]
	s_waitcnt lgkmcnt(0)
	v_mfma_f32_16x16x32_bf16 v[84:87], v[80:83], v[16:19], v[84:87]
	v_mfma_f32_16x16x32_bf16 v[68:71], v[80:83], v[20:23], v[68:71]
	ds_read_b128 v[72:75], v96 offset:6656
	ds_read_b128 v[80:83], v96 offset:6720
	ds_read_b128 v[88:91], v96 offset:6784
	s_waitcnt lgkmcnt(2)
	v_mfma_f32_16x16x32_bf16 v[92:95], v[72:75], v[0:3], 0
	v_mfma_f32_16x16x32_bf16 v[72:75], v[72:75], v[8:11], 0
	s_waitcnt lgkmcnt(1)
	v_mfma_f32_16x16x32_bf16 v[92:95], v[80:83], v[4:7], v[92:95]
	v_mfma_f32_16x16x32_bf16 v[72:75], v[80:83], v[12:15], v[72:75]
	s_waitcnt lgkmcnt(0)
	v_mfma_f32_16x16x32_bf16 v[92:95], v[88:91], v[16:19], v[92:95]
	v_mfma_f32_16x16x32_bf16 v[72:75], v[88:91], v[20:23], v[72:75]
	ds_read_b128 v[80:83], v96 offset:9984
	ds_read_b128 v[88:91], v96 offset:10048
	ds_read_b128 v[96:99], v96 offset:10112
	s_waitcnt lgkmcnt(2)
	v_mfma_f32_16x16x32_bf16 v[0:3], v[80:83], v[0:3], 0
	s_waitcnt lgkmcnt(1)
	v_mfma_f32_16x16x32_bf16 v[0:3], v[88:91], v[4:7], v[0:3]
	v_mfma_f32_16x16x32_bf16 v[4:7], v[80:83], v[8:11], 0
	v_add_f32_e64 v8, v76, -v130
	v_add_f32_e64 v9, v77, -v131
	v_pk_add_f32 v[10:11], v[78:79], v[130:131] neg_lo:[0,1] neg_hi:[0,1]
	s_waitcnt lgkmcnt(0)
	v_mfma_f32_16x16x32_bf16 v[0:3], v[96:99], v[16:19], v[0:3]
	v_mfma_f32_16x16x32_bf16 v[4:7], v[88:91], v[12:15], v[4:7]
	v_exp_f32_e32 v12, v8
	v_exp_f32_e32 v13, v9
	v_exp_f32_e32 v14, v10
	v_exp_f32_e32 v15, v11
	v_pk_add_f32 v[8:9], v[84:85], v[130:131] neg_lo:[0,1] neg_hi:[0,1]
	v_pk_add_f32 v[10:11], v[86:87], v[130:131] neg_lo:[0,1] neg_hi:[0,1]
	s_nop 0
	v_pk_add_f32 v[0:1], v[0:1], v[130:131] neg_lo:[0,1] neg_hi:[0,1]
	v_pk_add_f32 v[2:3], v[2:3], v[130:131] neg_lo:[0,1] neg_hi:[0,1]
	v_mfma_f32_16x16x32_bf16 v[4:7], v[96:99], v[20:23], v[4:7]
	v_exp_f32_e32 v18, v8
	v_exp_f32_e32 v19, v9
	v_exp_f32_e32 v20, v10
	v_exp_f32_e32 v21, v11
	v_pk_add_f32 v[8:9], v[92:93], v[130:131] neg_lo:[0,1] neg_hi:[0,1]
	v_pk_add_f32 v[10:11], v[94:95], v[130:131] neg_lo:[0,1] neg_hi:[0,1]
	v_exp_f32_e32 v0, v0
	v_exp_f32_e32 v1, v1
	v_exp_f32_e32 v2, v2
	v_exp_f32_e32 v3, v3
	v_exp_f32_e32 v8, v8
	v_exp_f32_e32 v9, v9
	v_exp_f32_e32 v10, v10
	v_exp_f32_e32 v11, v11
	v_cvt_pk_bf16_f32 v16, v12, v13
	v_cvt_pk_bf16_f32 v17, v14, v15
	v_cvt_pk_bf16_f32 v18, v18, v19
	v_cvt_pk_bf16_f32 v19, v20, v21
	v_cvt_pk_bf16_f32 v20, v8, v9
	v_cvt_pk_bf16_f32 v21, v10, v11
	v_cvt_pk_bf16_f32 v22, v0, v1
	v_cvt_pk_bf16_f32 v23, v2, v3
	v_pk_add_f32 v[0:1], v[64:65], v[128:129] neg_lo:[0,1] neg_hi:[0,1]
	v_pk_add_f32 v[2:3], v[66:67], v[128:129] neg_lo:[0,1] neg_hi:[0,1]
	v_exp_f32_e32 v8, v0
	v_exp_f32_e32 v9, v1
	v_exp_f32_e32 v10, v2
	v_exp_f32_e32 v11, v3
	v_pk_add_f32 v[0:1], v[68:69], v[128:129] neg_lo:[0,1] neg_hi:[0,1]
	v_pk_add_f32 v[2:3], v[70:71], v[128:129] neg_lo:[0,1] neg_hi:[0,1]
	v_exp_f32_e32 v12, v0
	v_exp_f32_e32 v13, v1
	v_exp_f32_e32 v14, v2
	v_exp_f32_e32 v15, v3
	v_pk_add_f32 v[0:1], v[72:73], v[128:129] neg_lo:[0,1] neg_hi:[0,1]
	v_pk_add_f32 v[2:3], v[74:75], v[128:129] neg_lo:[0,1] neg_hi:[0,1]
	v_exp_f32_e32 v68, v0
	v_exp_f32_e32 v69, v1
	v_exp_f32_e32 v70, v2
	v_exp_f32_e32 v71, v3
	v_pk_add_f32 v[0:1], v[4:5], v[128:129] neg_lo:[0,1] neg_hi:[0,1]
	v_pk_add_f32 v[2:3], v[6:7], v[128:129] neg_lo:[0,1] neg_hi:[0,1]
	v_add3_u32 v72, s10, v138, v143
	v_exp_f32_e32 v0, v0
	v_exp_f32_e32 v1, v1
	v_exp_f32_e32 v2, v2
	v_exp_f32_e32 v3, v3
	v_cvt_pk_bf16_f32 v64, v8, v9
	v_add_u32_e32 v8, 0x3000, v72
	v_cvt_pk_bf16_f32 v65, v10, v11
	v_cvt_pk_bf16_f32 v66, v12, v13
	v_cvt_pk_bf16_f32 v67, v14, v15
	v_cvt_pk_bf16_f32 v68, v68, v69
	v_cvt_pk_bf16_f32 v69, v70, v71
	v_cvt_pk_bf16_f32 v70, v0, v1
	v_cvt_pk_bf16_f32 v71, v2, v3
	ds_read2_b64 v[0:3], v8 offset0:128 offset1:132
	ds_read2_b64 v[8:11], v8 offset0:136 offset1:140
	s_waitcnt lgkmcnt(1)
	v_mfma_f32_16x16x32_bf16 v[4:7], v[0:3], v[16:19], v[60:63]
	v_add_u32_e32 v12, 0x3800, v72
	s_lshl_b32 s10, s24, 7
	s_cmp_ge_i32 s9, s19
	v_mfma_f32_16x16x32_bf16 v[0:3], v[0:3], v[64:67], v[56:59]
	s_waitcnt lgkmcnt(0)
	v_mfma_f32_16x16x32_bf16 v[56:59], v[8:11], v[20:23], v[4:7]
	s_nop 2
	ds_read2_b64 v[4:7], v12 offset0:160 offset1:164
	ds_read2_b64 v[12:15], v12 offset0:168 offset1:172
	v_mfma_f32_16x16x32_bf16 v[0:3], v[8:11], v[68:71], v[0:3]
	s_waitcnt lgkmcnt(1)
	v_mfma_f32_16x16x32_bf16 v[8:11], v[4:7], v[16:19], v[52:55]
	s_nop 2
	v_add_u32_e32 v52, 0x4000, v72
	v_mfma_f32_16x16x32_bf16 v[4:7], v[4:7], v[64:67], v[48:51]
	s_waitcnt lgkmcnt(0)
	v_mfma_f32_16x16x32_bf16 v[48:51], v[12:15], v[20:23], v[8:11]
	s_nop 2
	ds_read2_b64 v[8:11], v52 offset0:192 offset1:196
	v_mfma_f32_16x16x32_bf16 v[4:7], v[12:15], v[68:71], v[4:7]
	s_waitcnt lgkmcnt(0)
	v_mfma_f32_16x16x32_bf16 v[12:15], v[8:11], v[16:19], v[44:47]
	v_mfma_f32_16x16x32_bf16 v[8:11], v[8:11], v[64:67], v[40:43]
	s_nop 2
	ds_read2_b64 v[40:43], v52 offset0:200 offset1:204
	s_waitcnt lgkmcnt(0)
	v_mfma_f32_16x16x32_bf16 v[44:47], v[40:43], v[20:23], v[12:15]
	v_mfma_f32_16x16x32_bf16 v[12:15], v[40:43], v[68:71], v[8:11]
	v_add_u32_e32 v40, 0x4800, v72
	s_nop 1
	ds_read2_b64 v[8:11], v40 offset0:224 offset1:228
	ds_read2_b64 v[40:43], v40 offset0:232 offset1:236
	s_waitcnt lgkmcnt(1)
	v_mfma_f32_16x16x32_bf16 v[36:39], v[8:11], v[16:19], v[36:39]
	s_waitcnt lgkmcnt(0)
	s_barrier
	v_mfma_f32_16x16x32_bf16 v[8:11], v[8:11], v[64:67], v[32:35]
	v_mfma_f32_16x16x32_bf16 v[32:35], v[40:43], v[20:23], v[36:39]
	s_nop 3
	v_mov_b64_e32 v[36:37], s[52:53]
	v_mov_b64_e32 v[38:39], s[54:55]
	v_mfma_f32_16x16x32_bf16 v[8:11], v[40:43], v[68:71], v[8:11]
	s_nop 0
	v_mfma_f32_16x16x32_bf16 v[16:19], v[36:39], v[16:19], v[28:31]
	v_mfma_f32_16x16x32_bf16 v[24:27], v[36:39], v[64:67], v[24:27]
	v_mfma_f32_16x16x32_bf16 v[16:19], v[36:39], v[20:23], v[16:19]
	v_mfma_f32_16x16x32_bf16 v[18:21], v[36:39], v[68:71], v[24:27]
	s_nop 6
	v_div_scale_f32 v17, s[2:3], v16, v16, 1.0
	v_rcp_f32_e32 v19, v17
	v_add_u32_e32 v20, s25, v117
	v_fma_f32 v21, -v17, v19, 1.0
	v_fmac_f32_e32 v19, v21, v19
	v_div_scale_f32 v21, vcc, 1.0, v16, 1.0
	v_mul_f32_e32 v22, v21, v19
	v_fma_f32 v23, -v17, v22, v21
	v_fmac_f32_e32 v22, v23, v19
	v_fma_f32 v17, -v17, v22, v21
	v_ashrrev_i32_e32 v21, 31, v20
	v_div_fmas_f32 v17, v17, v19, v22
	v_lshlrev_b64 v[22:23], 11, v[20:21]
	v_div_fixup_f32 v16, v17, v16, 1.0
	v_lshl_add_u64 v[22:23], s[58:59], 0, v[22:23]
	v_lshl_add_u64 v[22:23], v[22:23], 0, s[10:11]
	v_pk_mul_f32 v[26:27], v[56:57], v[16:17] op_sel_hi:[1,0]
	v_lshl_add_u64 v[22:23], v[22:23], 0, v[126:127]
	v_pk_mul_f32 v[24:25], v[58:59], v[16:17] op_sel_hi:[1,0]
	v_cvt_pk_bf16_f32 v26, v26, v27
	s_nop 0
	v_cvt_pk_bf16_f32 v27, v24, v25
	global_store_dwordx2 v[22:23], v[26:27], off offset:512
	v_pk_mul_f32 v[26:27], v[48:49], v[16:17] op_sel_hi:[1,0]
	v_pk_mul_f32 v[24:25], v[50:51], v[16:17] op_sel_hi:[1,0]
	v_cvt_pk_bf16_f32 v26, v26, v27
	s_nop 0
	v_cvt_pk_bf16_f32 v27, v24, v25
	global_store_dwordx2 v[22:23], v[26:27], off offset:544
	v_pk_mul_f32 v[24:25], v[46:47], v[16:17] op_sel_hi:[1,0]
	v_pk_mul_f32 v[26:27], v[44:45], v[16:17] op_sel_hi:[1,0]
	s_nop 0
	v_cvt_pk_bf16_f32 v26, v26, v27
	v_cvt_pk_bf16_f32 v27, v24, v25
	v_pk_mul_f32 v[24:25], v[34:35], v[16:17] op_sel_hi:[1,0]
	v_pk_mul_f32 v[16:17], v[32:33], v[16:17] op_sel_hi:[1,0]
	global_store_dwordx2 v[22:23], v[26:27], off offset:576
	v_cvt_pk_bf16_f32 v16, v16, v17
	v_cvt_pk_bf16_f32 v17, v24, v25
	global_store_dwordx2 v[22:23], v[16:17], off offset:608
	v_div_scale_f32 v16, s[2:3], v18, v18, 1.0
	v_rcp_f32_e32 v17, v16
	s_nop 0
	v_fma_f32 v19, -v16, v17, 1.0
	v_fmac_f32_e32 v17, v19, v17
	v_div_scale_f32 v19, vcc, 1.0, v18, 1.0
	v_mul_f32_e32 v21, v19, v17
	v_fma_f32 v22, -v16, v21, v19
	v_fmac_f32_e32 v21, v22, v17
	v_fma_f32 v16, -v16, v21, v19
	v_div_fmas_f32 v16, v16, v17, v21
	v_div_fixup_f32 v16, v16, v18, 1.0
	v_add_u32_e32 v18, 16, v20
	v_ashrrev_i32_e32 v19, 31, v18
	v_lshlrev_b64 v[18:19], 11, v[18:19]
	v_lshl_add_u64 v[18:19], s[58:59], 0, v[18:19]
	v_lshl_add_u64 v[18:19], v[18:19], 0, s[10:11]
	v_pk_mul_f32 v[2:3], v[2:3], v[16:17] op_sel_hi:[1,0]
	v_pk_mul_f32 v[0:1], v[0:1], v[16:17] op_sel_hi:[1,0]
	v_lshl_add_u64 v[18:19], v[18:19], 0, v[126:127]
	v_cvt_pk_bf16_f32 v0, v0, v1
	v_cvt_pk_bf16_f32 v1, v2, v3
	v_pk_mul_f32 v[2:3], v[4:5], v[16:17] op_sel_hi:[1,0]
	global_store_dwordx2 v[18:19], v[0:1], off offset:512
	v_pk_mul_f32 v[0:1], v[6:7], v[16:17] op_sel_hi:[1,0]
	v_cvt_pk_bf16_f32 v2, v2, v3
	s_nop 0
	v_cvt_pk_bf16_f32 v3, v0, v1
	global_store_dwordx2 v[18:19], v[2:3], off offset:544
	v_pk_mul_f32 v[2:3], v[12:13], v[16:17] op_sel_hi:[1,0]
	v_pk_mul_f32 v[0:1], v[14:15], v[16:17] op_sel_hi:[1,0]
	v_cvt_pk_bf16_f32 v2, v2, v3
	s_nop 0
	v_cvt_pk_bf16_f32 v3, v0, v1
	global_store_dwordx2 v[18:19], v[2:3], off offset:576
	v_pk_mul_f32 v[2:3], v[8:9], v[16:17] op_sel_hi:[1,0]
	v_pk_mul_f32 v[0:1], v[10:11], v[16:17] op_sel_hi:[1,0]
	v_cvt_pk_bf16_f32 v2, v2, v3
	s_nop 0
	v_cvt_pk_bf16_f32 v3, v0, v1
	global_store_dwordx2 v[18:19], v[2:3], off offset:608
	s_cbranch_scc1 .LBB0_181

.LBB0_173:
	s_or_b64 exec, exec, s[6:7]
	s_add_i32 s6, s34, 1
	s_waitcnt vmcnt(1)
	v_add_u32_e32 v24, 0, v116
	s_add_u32 s34, s21, s35
	v_mov_b32_e32 v26, v157
	v_mov_b32_e32 v27, v157
	s_waitcnt vmcnt(0)
	ds_write_b128 v24, v[28:31] offset:13312
	s_addc_u32 s35, s10, 0
	v_mov_b32_e32 v24, v157
	v_mov_b32_e32 v25, v157
	v_mov_b64_e32 v[30:31], v[26:27]
	v_mov_b64_e32 v[34:35], v[26:27]
	v_mov_b64_e32 v[38:39], v[26:27]
	v_mov_b64_e32 v[42:43], v[26:27]
	v_mov_b64_e32 v[46:47], v[26:27]
	v_mov_b64_e32 v[50:51], v[26:27]
	v_mov_b64_e32 v[54:55], v[26:27]
	v_mov_b64_e32 v[58:59], v[26:27]
	v_mov_b64_e32 v[62:63], v[26:27]
	v_lshl_add_u64 v[132:133], v[120:121], 0, s[34:35]
	v_lshl_add_u64 v[134:135], v[122:123], 0, s[2:3]
	v_lshl_add_u64 v[136:137], v[124:125], 0, s[2:3]
	s_mov_b32 s7, 0
	v_mov_b32_e32 v128, 0xf149f2ca
	v_mov_b64_e32 v[28:29], v[24:25]
	v_mov_b64_e32 v[32:33], v[24:25]
	v_mov_b64_e32 v[36:37], v[24:25]
	v_mov_b64_e32 v[40:41], v[24:25]
	v_mov_b64_e32 v[44:45], v[24:25]
	v_mov_b64_e32 v[48:49], v[24:25]
	v_mov_b64_e32 v[52:53], v[24:25]
	v_mov_b64_e32 v[56:57], v[24:25]
	v_mov_b64_e32 v[60:61], v[24:25]
	v_mov_b32_e32 v130, 0xf149f2ca
	s_waitcnt lgkmcnt(0)
	s_barrier
	v_mov_b32_e32 v250, s52
	v_mov_b32_e32 v251, s52
	v_mov_b32_e32 v252, s52
	v_mov_b32_e32 v253, s52
	s_branch .LBB0_175
